# attention sample units: q rows, sink and gates loaded together with the K/V window (hoisted above the staging wait)
# baseline (speedup 1.0000x reference)
.LBB0_569:
	s_add_i32 s10, s17, 0xfffff7e0
	s_and_b32 s18, s17, 7
	s_and_b32 s6, s10, -8
	s_barrier
	s_and_saveexec_b64 s[8:9], s[38:39]
	s_cbranch_execz .LBB0_586
	s_lshl_b32 s10, s10, 7
	s_and_b32 s19, s10, 0xfffffc00
	v_readlane_b32 s10, v253, 63
	v_readlane_b32 s11, v254, 0
	s_lshl_b32 s10, s18, 7
	s_mov_b32 s3, s11
	s_add_i32 s7, s6, 0x1fc0
	s_lshl_b32 s20, s18, 6
	s_or_b32 s21, s19, s18
	v_writelane_b32 v253, s2, 63
	v_lshl_add_u64 v[0:1], v[22:23], 0, s[10:11]
	v_writelane_b32 v254, s3, 0
	v_and_b32_e32 v128, -8, v76
	v_add_u32_e32 v128, s21, v128
	v_ashrrev_i32_e32 v129, 31, v128
	v_lshlrev_b64 v[128:129], 8, v[128:129]
	v_lshl_add_u64 v[128:129], v[26:27], 0, v[128:129]
	global_load_dwordx4 v[84:87], v[128:129], off
	global_load_dwordx4 v[88:91], v[128:129], off offset:16
	s_mov_b64 s[14:15], 0x20000
	v_lshl_add_u64 v[130:131], v[128:129], 0, s[14:15]
	global_load_dwordx4 v[92:95], v[130:131], off
	global_load_dwordx4 v[96:99], v[130:131], off offset:16
	v_and_b32_e32 v132, 0xffffffc0, v76
	v_add_u32_e32 v132, s19, v132
	v_or_b32_e32 v132, s18, v132
	v_ashrrev_i32_e32 v133, 31, v132
	v_lshlrev_b64 v[132:133], 8, v[132:133]
	v_lshl_add_u64 v[132:133], v[28:29], 0, v[132:133]
	s_mov_b64 s[12:13], 0x1000
	global_load_dword v108, v[132:133], off
	global_load_dword v109, v[132:133], off offset:2048
	v_lshl_add_u64 v[134:135], v[132:133], 0, s[12:13]
	global_load_dword v110, v[134:135], off
	global_load_dword v111, v[134:135], off offset:2048
	v_lshl_add_u64 v[134:135], v[134:135], 0, s[12:13]
	global_load_dword v112, v[134:135], off
	global_load_dword v113, v[134:135], off offset:2048
	v_lshl_add_u64 v[134:135], v[134:135], 0, s[12:13]
	global_load_dword v114, v[134:135], off
	global_load_dword v115, v[134:135], off offset:2048
	v_lshl_add_u64 v[132:133], v[132:133], 0, s[14:15]
	global_load_dword v116, v[132:133], off
	global_load_dword v117, v[132:133], off offset:2048
	v_lshl_add_u64 v[134:135], v[132:133], 0, s[12:13]
	global_load_dword v118, v[134:135], off
	global_load_dword v119, v[134:135], off offset:2048
	v_lshl_add_u64 v[134:135], v[134:135], 0, s[12:13]
	global_load_dword v120, v[134:135], off
	global_load_dword v121, v[134:135], off offset:2048
	v_lshl_add_u64 v[134:135], v[134:135], 0, s[12:13]
	global_load_dword v122, v[134:135], off
	global_load_dword v123, v[134:135], off offset:2048
	v_mov_b32_e32 v104, 0
	v_mov_b32_e32 v105, 0
	v_mov_b32_e32 v106, 0
	v_mov_b32_e32 v107, 0
	v_mov_b32_e32 v124, 0
	v_mov_b32_e32 v125, 0
	v_mov_b32_e32 v126, 0
	v_mov_b32_e32 v127, 0
	v_cmp_gt_u32_e32 vcc, 64, v76
	s_and_saveexec_b64 s[12:13], vcc
	v_lshrrev_b32_e32 v142, 3, v76
	v_add_u32_e32 v142, 0x80, v142
	v_add_u32_e32 v142, s7, v142
	v_ashrrev_i32_e32 v143, 31, v142
	v_lshlrev_b64 v[142:143], 10, v[142:143]
	v_lshl_add_u64 v[142:143], v[0:1], 0, v[142:143]
	global_load_dwordx4 v[104:107], v[142:143], off
	v_or_b32_e32 v144, s20, v35
	v_mul_u32_u24_e32 v144, 0x2200, v144
	v_readlane_b32 s10, v252, 31
	v_lshlrev_b32_e32 v144, 1, v144
	v_mov_b32_e32 v145, v2
	v_readlane_b32 s11, v252, 32
	s_ashr_i32 s7, s6, 31
	s_nop 1
	v_lshl_add_u64 v[144:145], s[10:11], 0, v[144:145]
	v_lshl_add_u64 v[144:145], s[6:7], 1, v[144:145]
	s_mov_b64 s[10:11], 0x4080
	v_lshl_add_u64 v[144:145], v[144:145], 0, s[10:11]
	global_load_dwordx4 v[124:127], v[144:145], off
	s_or_b64 exec, exec, s[12:13]
	v_lshrrev_b32_e32 v146, 3, v76
	s_movk_i32 s3, 0x90
	v_mad_u32_u24 v146, v146, s3, v24
	v_lshrrev_b32_e32 v147, 6, v76
	v_lshl_add_u32 v147, v147, 4, v36
	s_lshl_b32 s12, s18, 3
	s_add_i32 s12, s12, s68
	s_add_i32 s14, s12, s16
	s_ashr_i32 s15, s14, 31
	s_lshl_b64 s[14:15], s[14:15], 2
	v_readlane_b32 s10, v251, 18
	v_readlane_b32 s11, v251, 19
	s_nop 1
	s_add_u32 s14, s10, s14
	s_addc_u32 s15, s11, s15
	global_load_dword v3, v2, s[14:15]
	v_add_u32_e32 v148, s6, v37
	v_ashrrev_i32_e32 v149, 31, v148
	v_lshlrev_b64 v[150:151], 13, v[148:149]
	s_lshl_b32 s12, s12, 6
	s_ashr_i32 s13, s12, 31
	v_lshl_add_u64 v[4:5], s[12:13], 1, v[20:21]
	v_lshl_add_u64 v[8:9], v[4:5], 0, v[150:151]
	global_load_dwordx4 v[4:7], v[8:9], off
	s_nop 0
	global_load_dwordx4 v[8:11], v[8:9], off offset:64
	v_lshlrev_b64 v[152:153], 12, v[148:149]
	v_lshl_add_u64 v[152:153], v[152:153], 0, s[12:13]
	v_or_b32_e32 v152, v152, v78
	v_lshlrev_b64 v[152:153], 1, v[152:153]
	v_readlane_b32 s10, v251, 22
	v_readlane_b32 s11, v251, 23
	v_mbcnt_lo_u32_b32 v154, -1, 0
	v_mbcnt_hi_u32_b32 v154, -1, v154
	v_and_b32_e32 v154, 16, v154
	v_lshrrev_b32_e32 v155, 1, v154
	v_add_u32_e32 v154, v154, v155
	v_mov_b32_e32 v155, 0
	v_lshl_add_u64 v[152:153], s[10:11], 0, v[152:153]
	v_lshl_add_u64 v[152:153], v[154:155], 0, v[152:153]
	global_load_dwordx4 v[156:159], v[152:153], off
	global_load_dwordx4 v[164:167], v[152:153], off offset:64
	s_waitcnt vmcnt(0)
	v_cvt_pk_bf16_f32 v84, v84, v85
	v_cvt_pk_bf16_f32 v85, v86, v87
	v_cvt_pk_bf16_f32 v86, v88, v89
	v_cvt_pk_bf16_f32 v87, v90, v91
	v_cvt_pk_bf16_f32 v92, v92, v93
	v_cvt_pk_bf16_f32 v93, v94, v95
	v_cvt_pk_bf16_f32 v94, v96, v97
	v_cvt_pk_bf16_f32 v95, v98, v99
	ds_write_b128 v146, v[84:87]
	ds_write_b128 v146, v[92:95] offset:9216
	v_cvt_pk_bf16_f32 v108, v108, v109
	v_cvt_pk_bf16_f32 v109, v110, v111
	v_cvt_pk_bf16_f32 v110, v112, v113
	v_cvt_pk_bf16_f32 v111, v114, v115
	v_cvt_pk_bf16_f32 v116, v116, v117
	v_cvt_pk_bf16_f32 v117, v118, v119
	v_cvt_pk_bf16_f32 v118, v120, v121
	v_cvt_pk_bf16_f32 v119, v122, v123
	ds_write_b128 v147, v[108:111] offset:23040
	ds_write_b128 v147, v[116:119] offset:23168
	v_cmp_gt_u32_e32 vcc, 0x100, v76
	s_and_b64 exec, exec, vcc
	ds_write_b128 v146, v[104:107] offset:18432
	ds_write_b128 v147, v[124:127] offset:23296
.LBB0_586:
	s_or_b64 exec, exec, s[8:9]
	s_lshl_b32 s7, s18, 3
	s_add_i32 s7, s7, s68
	s_add_i32 s8, s7, 1
	v_cvt_f32_i32_e32 v0, s8
	v_readlane_b32 s76, v251, 4
	v_readlane_b32 s90, v251, 18
	v_readlane_b32 s91, v251, 19
	v_mul_f32_e32 v1, 0xbe000000, v0
	v_cmp_gt_f32_e32 vcc, s94, v1
	s_and_b64 s[8:9], vcc, exec
	s_cselect_b32 s8, 0xffffffc0, 0
	v_cndmask_b32_e32 v1, 0, v213, vcc
	v_fmac_f32_e32 v1, 0xbe000000, v0
	v_exp_f32_e32 v0, v1
	v_add_u32_e32 v30, s6, v37
	v_ashrrev_i32_e32 v31, 31, v30
	v_ldexp_f32 v1, v0, s8
	s_add_i32 s8, s7, s16
	s_ashr_i32 s9, s8, 31
	s_lshl_b64 s[8:9], s[8:9], 2
	s_add_u32 s8, s90, s8
	s_addc_u32 s9, s91, s9
	s_lshl_b32 s6, s7, 6
	s_ashr_i32 s7, s6, 31
	s_waitcnt lgkmcnt(0)
	s_barrier
	ds_read_b128 v[12:15], v38
	ds_read_b128 v[16:19], v38 offset:64
	v_readlane_b32 s77, v251, 5
	v_readlane_b32 s78, v251, 6
	v_readlane_b32 s79, v251, 7
	v_readlane_b32 s80, v251, 8
	v_readlane_b32 s81, v251, 9
	v_readlane_b32 s82, v251, 10
	v_readlane_b32 s83, v251, 11
	v_readlane_b32 s84, v251, 12
	v_readlane_b32 s85, v251, 13
	v_readlane_b32 s86, v251, 14
	v_readlane_b32 s87, v251, 15
	v_readlane_b32 s88, v251, 16
	v_readlane_b32 s89, v251, 17
	v_mul_f32_e32 v0, 0x3fb8aa3b, v1
	s_waitcnt vmcnt(1) lgkmcnt(1)
	v_mfma_f32_16x16x32_bf16 v[12:15], v[12:15], v[4:7], 0
	v_mul_f32_e32 v40, 0x3fb8aa3b, v3
	s_waitcnt vmcnt(0) lgkmcnt(0)
	v_mfma_f32_16x16x32_bf16 v[12:15], v[16:19], v[8:11], v[12:15]
	ds_read_b128 v[16:19], v38 offset:2304
	ds_read_b128 v[42:45], v38 offset:2368
	s_waitcnt lgkmcnt(1)
	v_mfma_f32_16x16x32_bf16 v[16:19], v[16:19], v[4:7], 0
	s_waitcnt lgkmcnt(0)
	v_mfma_f32_16x16x32_bf16 v[16:19], v[42:45], v[8:11], v[16:19]
	ds_read_b128 v[42:45], v38 offset:4608
	ds_read_b128 v[46:49], v38 offset:4672
	s_waitcnt lgkmcnt(1)
	v_mfma_f32_16x16x32_bf16 v[42:45], v[42:45], v[4:7], 0
	s_waitcnt lgkmcnt(0)
	v_mfma_f32_16x16x32_bf16 v[42:45], v[46:49], v[8:11], v[42:45]
	ds_read_b128 v[46:49], v38 offset:6912
	ds_read_b128 v[50:53], v38 offset:6976
	s_waitcnt lgkmcnt(1)
	v_mfma_f32_16x16x32_bf16 v[46:49], v[46:49], v[4:7], 0
	s_waitcnt lgkmcnt(0)
	v_mfma_f32_16x16x32_bf16 v[46:49], v[50:53], v[8:11], v[46:49]
	ds_read_b128 v[50:53], v38 offset:9216
	ds_read_b128 v[54:57], v38 offset:9280
	s_waitcnt lgkmcnt(1)
	v_mfma_f32_16x16x32_bf16 v[50:53], v[50:53], v[4:7], 0
	s_waitcnt lgkmcnt(0)
	v_mfma_f32_16x16x32_bf16 v[50:53], v[54:57], v[8:11], v[50:53]
	ds_read_b128 v[54:57], v38 offset:11520
	ds_read_b128 v[58:61], v38 offset:11584
	s_waitcnt lgkmcnt(1)
	v_mfma_f32_16x16x32_bf16 v[54:57], v[54:57], v[4:7], 0
	s_waitcnt lgkmcnt(0)
	v_mfma_f32_16x16x32_bf16 v[54:57], v[58:61], v[8:11], v[54:57]
	ds_read_b128 v[58:61], v38 offset:13824
	ds_read_b128 v[62:65], v38 offset:13888
	s_waitcnt lgkmcnt(1)
	v_mfma_f32_16x16x32_bf16 v[58:61], v[58:61], v[4:7], 0
	s_waitcnt lgkmcnt(0)
	v_mfma_f32_16x16x32_bf16 v[58:61], v[62:65], v[8:11], v[58:61]
	ds_read_b128 v[62:65], v38 offset:16128
	ds_read_b128 v[66:69], v38 offset:16192
	s_waitcnt lgkmcnt(1)
	v_mfma_f32_16x16x32_bf16 v[62:65], v[62:65], v[4:7], 0
	s_waitcnt lgkmcnt(0)
	v_mfma_f32_16x16x32_bf16 v[62:65], v[66:69], v[8:11], v[62:65]
	ds_read_b128 v[66:69], v38 offset:18432
	ds_read_b128 v[70:73], v38 offset:18496
	s_mov_b32 s8, 0xf149f2ca
	v_add_u32_e32 v80, 0x5800, v39
	v_add_u32_e32 v81, 0x8000, v39
	s_waitcnt lgkmcnt(1)
	v_mfma_f32_16x16x32_bf16 v[4:7], v[66:69], v[4:7], 0
	v_add_u32_e32 v82, 0x9800, v39
	s_waitcnt lgkmcnt(0)
	v_mfma_f32_16x16x32_bf16 v[4:7], v[70:73], v[8:11], v[4:7]
	v_mul_f32_e64 v8, v0, v160
	v_mul_f32_e64 v9, v0, v161
	v_sub_f32_e32 v3, v12, v9
	v_sub_f32_e32 v10, v13, v9
	v_fmac_f32_e32 v3, 0, v0
	v_fmac_f32_e32 v10, 0x3fb8aa3b, v1
	v_sub_f32_e32 v11, v14, v9
	v_sub_f32_e32 v12, v15, v9
	v_cndmask_b32_e64 v3, v214, v3, s[40:41]
	v_cndmask_b32_e64 v1, v214, v10, s[42:43]
	v_fmac_f32_e32 v11, 2.0, v0
	v_fmac_f32_e32 v12, 0x40400000, v0
	v_max3_f32 v10, v3, s8, v1
	v_cndmask_b32_e64 v11, v214, v11, s[44:45]
	v_cndmask_b32_e64 v12, v214, v12, s[0:1]
	v_sub_f32_e32 v13, v16, v9
	v_sub_f32_e32 v14, v17, v9
	v_max3_f32 v10, v10, v11, v12
	v_fmac_f32_e32 v13, 0x41800000, v0
	v_fmac_f32_e32 v14, 0x41880000, v0
	v_sub_f32_e32 v15, v18, v9
	v_sub_f32_e32 v16, v19, v9
	v_max3_f32 v10, v10, v13, v14
	v_fmac_f32_e32 v15, 0x41900000, v0
	v_fmac_f32_e32 v16, 0x41980000, v0
	v_sub_f32_e32 v17, v42, v9
	v_sub_f32_e32 v18, v43, v9
	v_max3_f32 v10, v10, v15, v16
	v_fmac_f32_e32 v17, 0x42000000, v0
	v_fmac_f32_e32 v18, 0x42040000, v0
	v_sub_f32_e32 v19, v44, v9
	v_sub_f32_e32 v32, v45, v9
	v_max3_f32 v10, v10, v17, v18
	v_fmac_f32_e32 v19, 0x42080000, v0
	v_fmac_f32_e32 v32, 0x420c0000, v0
	v_sub_f32_e32 v33, v46, v9
	v_sub_f32_e32 v42, v47, v9
	v_max3_f32 v10, v10, v19, v32
	v_fmac_f32_e32 v33, 0x42400000, v0
	v_fmac_f32_e32 v42, 0x42440000, v0
	v_sub_f32_e32 v43, v48, v9
	v_sub_f32_e32 v44, v49, v9
	v_max3_f32 v10, v10, v33, v42
	v_fmac_f32_e32 v43, 0x42480000, v0
	v_fmac_f32_e32 v44, 0x424c0000, v0
	v_sub_f32_e32 v45, v50, v9
	v_sub_f32_e32 v46, v51, v9
	v_max3_f32 v10, v10, v43, v44
	v_fmac_f32_e32 v45, 0x42800000, v0
	v_fmac_f32_e32 v46, 0x42820000, v0
	v_sub_f32_e32 v47, v52, v9
	v_sub_f32_e32 v48, v53, v9
	v_max3_f32 v10, v10, v45, v46
	v_fmac_f32_e32 v47, 0x42840000, v0
	v_fmac_f32_e32 v48, 0x42860000, v0
	v_sub_f32_e32 v49, v54, v9
	v_sub_f32_e32 v50, v55, v9
	v_max3_f32 v10, v10, v47, v48
	v_fmac_f32_e32 v49, 0x42a00000, v0
	v_fmac_f32_e32 v50, 0x42a20000, v0
	v_sub_f32_e32 v51, v56, v9
	v_sub_f32_e32 v52, v57, v9
	v_max3_f32 v10, v10, v49, v50
	v_fmac_f32_e32 v51, 0x42a40000, v0
	v_fmac_f32_e32 v52, 0x42a60000, v0
	v_sub_f32_e32 v53, v58, v9
	v_sub_f32_e32 v54, v59, v9
	v_max3_f32 v10, v10, v51, v52
	v_fmac_f32_e32 v53, 0x42c00000, v0
	v_fmac_f32_e32 v54, 0x42c20000, v0
	v_sub_f32_e32 v55, v60, v9
	v_sub_f32_e32 v56, v61, v9
	v_max3_f32 v10, v10, v53, v54
	v_fmac_f32_e32 v55, 0x42c40000, v0
	v_fmac_f32_e32 v56, 0x42c60000, v0
	v_sub_f32_e32 v57, v62, v9
	v_sub_f32_e32 v58, v63, v9
	v_sub_f32_e32 v6, v6, v9
	v_max3_f32 v10, v10, v55, v56
	v_fmac_f32_e32 v57, 0x42e00000, v0
	v_fmac_f32_e32 v58, 0x42e20000, v0
	v_sub_f32_e32 v59, v64, v9
	v_sub_f32_e32 v60, v65, v9
	v_sub_f32_e32 v4, v4, v9
	v_sub_f32_e32 v5, v5, v9
	v_fmac_f32_e32 v6, 0x43020000, v0
	v_max3_f32 v10, v10, v57, v58
	v_fmac_f32_e32 v59, 0x42e40000, v0
	v_fmac_f32_e32 v60, 0x42e60000, v0
	v_fmac_f32_e32 v4, 0x43000000, v0
	v_fmac_f32_e32 v5, 0x43010000, v0
	v_cndmask_b32_e64 v0, v214, v6, s[50:51]
	v_sub_f32_e32 v6, v7, v9
	v_max3_f32 v10, v10, v59, v60
	v_cndmask_b32_e64 v4, v4, v214, s[40:41]
	v_cndmask_b32_e64 v5, v214, v5, s[4:5]
	v_add_f32_e32 v6, v8, v6
	v_max3_f32 v10, v10, v4, v5
	v_cndmask_b32_e64 v6, v214, v6, s[52:53]
	v_max3_f32 v7, v10, v0, v6
	ds_bpermute_b32 v8, v25, v7
	s_waitcnt lgkmcnt(0)
	v_max_f32_e32 v8, v8, v8
	v_max_f32_e32 v7, v7, v8
	ds_bpermute_b32 v8, v34, v7
	s_waitcnt lgkmcnt(0)
	v_max3_f32 v41, v7, v8, v40
	v_sub_f32_e32 v3, v3, v41
	v_exp_f32_e32 v3, v3
	v_sub_f32_e32 v1, v1, v41
	v_exp_f32_e32 v1, v1
	v_sub_f32_e32 v8, v11, v41
	v_exp_f32_e32 v8, v8
	v_sub_f32_e32 v9, v12, v41
	v_exp_f32_e32 v9, v9
	v_sub_f32_e32 v10, v13, v41
	v_add_f32_e32 v7, 0, v3
	v_exp_f32_e32 v10, v10
	v_sub_f32_e32 v11, v14, v41
	v_add_f32_e32 v7, v1, v7
	v_exp_f32_e32 v11, v11
	v_sub_f32_e32 v12, v15, v41
	v_add_f32_e32 v7, v8, v7
	v_exp_f32_e32 v12, v12
	v_sub_f32_e32 v13, v16, v41
	v_add_f32_e32 v7, v9, v7
	v_exp_f32_e32 v13, v13
	v_sub_f32_e32 v14, v17, v41
	v_add_f32_e32 v7, v10, v7
	v_exp_f32_e32 v61, v14
	v_sub_f32_e32 v14, v18, v41
	v_add_f32_e32 v7, v11, v7
	v_exp_f32_e32 v62, v14
	v_sub_f32_e32 v14, v19, v41
	v_add_f32_e32 v7, v12, v7
	v_exp_f32_e32 v63, v14
	v_sub_f32_e32 v14, v32, v41
	v_add_f32_e32 v7, v13, v7
	v_exp_f32_e32 v32, v14
	v_sub_f32_e32 v14, v33, v41
	v_add_f32_e32 v7, v61, v7
	v_exp_f32_e32 v33, v14
	v_sub_f32_e32 v14, v42, v41
	v_add_f32_e32 v7, v62, v7
	v_exp_f32_e32 v64, v14
	v_sub_f32_e32 v14, v43, v41
	v_add_f32_e32 v7, v63, v7
	v_exp_f32_e32 v65, v14
	v_sub_f32_e32 v14, v44, v41
	v_add_f32_e32 v7, v32, v7
	v_exp_f32_e32 v66, v14
	v_sub_f32_e32 v14, v45, v41
	v_add_f32_e32 v7, v33, v7
	v_exp_f32_e32 v67, v14
	v_sub_f32_e32 v14, v46, v41
	v_add_f32_e32 v7, v64, v7
	v_exp_f32_e32 v68, v14
	v_sub_f32_e32 v14, v47, v41
	v_add_f32_e32 v7, v65, v7
	v_exp_f32_e32 v69, v14
	v_sub_f32_e32 v14, v48, v41
	v_add_f32_e32 v7, v66, v7
	v_exp_f32_e32 v70, v14
	v_sub_f32_e32 v14, v49, v41
	v_add_f32_e32 v7, v67, v7
	v_exp_f32_e32 v71, v14
	v_sub_f32_e32 v14, v50, v41
	v_add_f32_e32 v7, v68, v7
	v_exp_f32_e32 v72, v14
	v_sub_f32_e32 v14, v51, v41
	v_add_f32_e32 v7, v69, v7
	v_exp_f32_e32 v73, v14
	v_sub_f32_e32 v14, v52, v41
	v_add_f32_e32 v7, v70, v7
	v_exp_f32_e32 v52, v14
	v_sub_f32_e32 v14, v53, v41
	v_add_f32_e32 v7, v71, v7
	v_exp_f32_e32 v53, v14
	v_sub_f32_e32 v14, v54, v41
	v_add_f32_e32 v7, v72, v7
	v_exp_f32_e32 v54, v14
	v_sub_f32_e32 v14, v55, v41
	v_add_f32_e32 v7, v73, v7
	v_exp_f32_e32 v55, v14
	v_sub_f32_e32 v14, v56, v41
	v_add_f32_e32 v7, v52, v7
	v_exp_f32_e32 v56, v14
	v_sub_f32_e32 v14, v57, v41
	v_add_f32_e32 v7, v53, v7
	v_exp_f32_e32 v57, v14
	v_sub_f32_e32 v14, v58, v41
	v_add_f32_e32 v7, v54, v7
	v_exp_f32_e32 v58, v14
	v_sub_f32_e32 v14, v59, v41
	v_add_f32_e32 v7, v55, v7
	v_exp_f32_e32 v59, v14
	v_sub_f32_e32 v14, v60, v41
	v_add_f32_e32 v7, v56, v7
	v_exp_f32_e32 v60, v14
	v_sub_f32_e32 v4, v4, v41
	v_add_f32_e32 v7, v57, v7
	v_exp_f32_e32 v74, v4
	v_sub_f32_e32 v5, v5, v41
	v_add_f32_e32 v7, v58, v7
	v_exp_f32_e32 v75, v5
	v_sub_f32_e32 v0, v0, v41
	v_add_f32_e32 v7, v59, v7
	v_exp_f32_e32 v77, v0
	v_add_f32_e32 v7, v60, v7
	v_add_f32_e32 v4, v74, v7
	v_add_f32_e32 v4, v75, v4
	v_add_f32_e32 v0, v77, v4
	v_sub_f32_e32 v4, v6, v41
	v_exp_f32_e32 v79, v4
	v_cvt_pk_bf16_f32 v5, v8, v9
	v_cvt_pk_bf16_f32 v6, v10, v11
	v_cvt_pk_bf16_f32 v7, v12, v13
	v_add_f32_e32 v0, v79, v0
	ds_bpermute_b32 v4, v25, v0
	ds_read2_b64 v[8:11], v80 offset0:64 offset1:68
	ds_read2_b64 v[16:19], v81 offset0:128 offset1:132
	ds_read2_b64 v[44:47], v82 offset0:32 offset1:36
	s_waitcnt lgkmcnt(3)
	v_add_f32_e32 v42, v0, v4
	v_add_u32_e32 v0, 0x6800, v39
	ds_read2_b64 v[12:15], v0 offset0:224 offset1:228
	ds_bpermute_b32 v43, v34, v42
	v_cvt_pk_bf16_f32 v4, v3, v1
	s_waitcnt lgkmcnt(4)
	s_nop 0
	v_mfma_f32_16x16x32_bf16 v[8:11], v[8:11], v[4:7], 0
	s_waitcnt lgkmcnt(1)
	v_mfma_f32_16x16x32_bf16 v[12:15], v[12:15], v[4:7], 0
	v_mfma_f32_16x16x32_bf16 v[16:19], v[16:19], v[4:7], 0
	v_mfma_f32_16x16x32_bf16 v[4:7], v[44:47], v[4:7], 0
	ds_read2_b64 v[48:51], v80 offset0:72 offset1:76
	v_cvt_pk_bf16_f32 v44, v61, v62
	v_cvt_pk_bf16_f32 v45, v63, v32
	v_cvt_pk_bf16_f32 v46, v33, v64
	v_cvt_pk_bf16_f32 v47, v65, v66
	s_waitcnt lgkmcnt(0)
	s_nop 0
	v_mfma_f32_16x16x32_bf16 v[8:11], v[48:51], v[44:47], v[8:11]
	ds_read2_b64 v[48:51], v0 offset0:232 offset1:236
	s_waitcnt lgkmcnt(0)
	v_mfma_f32_16x16x32_bf16 v[12:15], v[48:51], v[44:47], v[12:15]
	ds_read2_b64 v[48:51], v81 offset0:136 offset1:140
	s_waitcnt lgkmcnt(0)
	v_mfma_f32_16x16x32_bf16 v[16:19], v[48:51], v[44:47], v[16:19]
	ds_read2_b64 v[48:51], v82 offset0:40 offset1:44
	s_waitcnt lgkmcnt(0)
	v_mfma_f32_16x16x32_bf16 v[4:7], v[48:51], v[44:47], v[4:7]
	ds_read2_b64 v[48:51], v80 offset0:80 offset1:84
	v_cvt_pk_bf16_f32 v44, v67, v68
	v_cvt_pk_bf16_f32 v45, v69, v70
	v_cvt_pk_bf16_f32 v46, v71, v72
	v_cvt_pk_bf16_f32 v47, v73, v52
	s_waitcnt lgkmcnt(0)
	s_nop 0
	v_mfma_f32_16x16x32_bf16 v[8:11], v[48:51], v[44:47], v[8:11]
	ds_read2_b64 v[48:51], v0 offset0:240 offset1:244
	s_waitcnt lgkmcnt(0)
	v_mfma_f32_16x16x32_bf16 v[12:15], v[48:51], v[44:47], v[12:15]
	ds_read2_b64 v[48:51], v81 offset0:144 offset1:148
	s_waitcnt lgkmcnt(0)
	v_mfma_f32_16x16x32_bf16 v[16:19], v[48:51], v[44:47], v[16:19]
	ds_read2_b64 v[48:51], v82 offset0:48 offset1:52
	s_waitcnt lgkmcnt(0)
	v_mfma_f32_16x16x32_bf16 v[4:7], v[48:51], v[44:47], v[4:7]
	ds_read2_b64 v[48:51], v80 offset0:88 offset1:92
	v_cvt_pk_bf16_f32 v44, v53, v54
	v_cvt_pk_bf16_f32 v45, v55, v56
	v_cvt_pk_bf16_f32 v46, v57, v58
	v_cvt_pk_bf16_f32 v47, v59, v60
	s_waitcnt lgkmcnt(0)
	s_nop 0
	v_mfma_f32_16x16x32_bf16 v[8:11], v[48:51], v[44:47], v[8:11]
	ds_read2_b64 v[48:51], v0 offset0:248 offset1:252
	s_waitcnt lgkmcnt(0)
	v_mfma_f32_16x16x32_bf16 v[12:15], v[48:51], v[44:47], v[12:15]
	ds_read2_b64 v[48:51], v81 offset0:152 offset1:156
	s_waitcnt lgkmcnt(0)
	v_mfma_f32_16x16x32_bf16 v[48:51], v[48:51], v[44:47], v[16:19]
	s_nop 2
	ds_read2_b64 v[16:19], v82 offset0:56 offset1:60
	s_waitcnt lgkmcnt(0)
	v_mfma_f32_16x16x32_bf16 v[4:7], v[16:19], v[44:47], v[4:7]
	ds_read2_b64 v[16:19], v80 offset0:96 offset1:100
	v_cvt_pk_bf16_f32 v0, v74, v75
	v_cvt_pk_bf16_f32 v1, v77, v79
	v_mov_b32_e32 v3, v2
	ds_read2_b64 v[44:47], v82 offset0:64 offset1:68
	s_waitcnt lgkmcnt(1)
	v_mfma_f32_16x16x32_bf16 v[16:19], v[16:19], v[0:3], v[8:11]
	s_nop 2
	v_add_u32_e32 v8, 0x7000, v39
	ds_read2_b64 v[8:11], v8 offset1:4
	s_waitcnt lgkmcnt(1)
	v_mfma_f32_16x16x32_bf16 v[4:7], v[44:47], v[0:3], v[4:7]
	s_waitcnt lgkmcnt(0)
	v_mfma_f32_16x16x32_bf16 v[12:15], v[8:11], v[0:3], v[12:15]
	ds_read2_b64 v[8:11], v81 offset0:160 offset1:164
	s_waitcnt lgkmcnt(0)
	v_mfma_f32_16x16x32_bf16 v[8:11], v[8:11], v[0:3], v[48:51]
	s_and_saveexec_b64 s[8:9], s[54:55]
	s_cbranch_execz .LBB0_568
	v_lshlrev_b64 v[0:1], 12, v[30:31]
	v_lshl_add_u64 v[0:1], v[0:1], 0, s[6:7]
	v_or_b32_e32 v0, v0, v78
	v_readlane_b32 s6, v253, 53
	v_sub_f32_e32 v3, v40, v41
	v_lshlrev_b64 v[30:31], 1, v[0:1]
	v_readlane_b32 s7, v253, 54
	v_exp_f32_e32 v3, v3
	s_nop 0
	v_lshl_add_u64 v[0:1], s[6:7], 0, v[30:31]
	v_readlane_b32 s6, v251, 22
	v_readlane_b32 s7, v251, 23
	s_nop 1
	v_lshl_add_u64 v[32:33], s[6:7], 0, v[30:31]
	v_add_f32_e32 v30, v42, v43
	v_add_f32_e32 v3, v3, v30
	v_div_scale_f32 v30, s[6:7], v3, v3, 1.0
	v_rcp_f32_e32 v31, v30
	s_nop 0
	v_fma_f32 v40, -v30, v31, 1.0
	v_fmac_f32_e32 v31, v40, v31
	v_div_scale_f32 v40, vcc, 1.0, v3, 1.0
	v_mul_f32_e32 v41, v40, v31
	v_fma_f32 v42, -v30, v41, v40
	v_fmac_f32_e32 v41, v42, v31
	v_fma_f32 v30, -v30, v41, v40
	v_div_fmas_f32 v30, v30, v31, v41
	v_mbcnt_lo_u32_b32 v40, -1, 0
	v_mbcnt_hi_u32_b32 v40, -1, v40
	v_and_b32_e32 v40, 16, v40
	v_lshrrev_b32_e32 v41, 1, v40
	v_add_u32_e32 v40, v40, v41
	v_mov_b32_e32 v41, 0
	v_lshl_add_u64 v[0:1], v[40:41], 0, v[0:1]
	v_div_fixup_f32 v30, v30, v3, 1.0
	v_pk_mul_f32 v[18:19], v[30:31], v[18:19] op_sel_hi:[0,1]
	v_pk_mul_f32 v[16:17], v[30:31], v[16:17] op_sel_hi:[0,1]
	v_pk_mul_f32 v[14:15], v[30:31], v[14:15] op_sel_hi:[0,1]
	v_pk_mul_f32 v[12:13], v[30:31], v[12:13] op_sel_hi:[0,1]
	v_pk_mul_f32 v[10:11], v[30:31], v[10:11] op_sel_hi:[0,1]
	v_pk_mul_f32 v[8:9], v[30:31], v[8:9] op_sel_hi:[0,1]
	v_pk_mul_f32 v[6:7], v[30:31], v[6:7] op_sel_hi:[0,1]
	v_pk_mul_f32 v[4:5], v[30:31], v[4:5] op_sel_hi:[0,1]
	s_waitcnt vmcnt(0)
	v_permlane16_swap_b32 v156, v158
	v_permlane16_swap_b32 v157, v159
	v_permlane16_swap_b32 v164, v166
	v_permlane16_swap_b32 v165, v167
	s_nop 1
	v_lshlrev_b32_e32 v42, 16, v156
	v_and_b32_e32 v43, 0xffff0000, v156
	v_pk_mul_f32 v[16:17], v[16:17], v[42:43]
	v_lshlrev_b32_e32 v42, 16, v157
	v_and_b32_e32 v43, 0xffff0000, v157
	v_pk_mul_f32 v[18:19], v[18:19], v[42:43]
	v_cvt_pk_bf16_f32 v16, v16, v17
	v_cvt_pk_bf16_f32 v17, v18, v19
	v_lshlrev_b32_e32 v42, 16, v158
	v_and_b32_e32 v43, 0xffff0000, v158
	v_pk_mul_f32 v[12:13], v[12:13], v[42:43]
	v_lshlrev_b32_e32 v42, 16, v159
	v_and_b32_e32 v43, 0xffff0000, v159
	v_pk_mul_f32 v[14:15], v[14:15], v[42:43]
	v_cvt_pk_bf16_f32 v18, v12, v13
	v_cvt_pk_bf16_f32 v19, v14, v15
	v_lshlrev_b32_e32 v42, 16, v164
	v_and_b32_e32 v43, 0xffff0000, v164
	v_pk_mul_f32 v[8:9], v[8:9], v[42:43]
	v_lshlrev_b32_e32 v42, 16, v165
	v_and_b32_e32 v43, 0xffff0000, v165
	v_pk_mul_f32 v[10:11], v[10:11], v[42:43]
	v_cvt_pk_bf16_f32 v8, v8, v9
	v_cvt_pk_bf16_f32 v9, v10, v11
	v_lshlrev_b32_e32 v42, 16, v166
	v_and_b32_e32 v43, 0xffff0000, v166
	v_pk_mul_f32 v[4:5], v[4:5], v[42:43]
	v_lshlrev_b32_e32 v42, 16, v167
	v_and_b32_e32 v43, 0xffff0000, v167
	v_pk_mul_f32 v[6:7], v[6:7], v[42:43]
	v_cvt_pk_bf16_f32 v10, v4, v5
	v_cvt_pk_bf16_f32 v11, v6, v7
	v_permlane16_swap_b32 v16, v18
	v_permlane16_swap_b32 v17, v19
	global_store_dwordx4 v[0:1], v[16:19], off
	v_permlane16_swap_b32 v8, v10
	v_permlane16_swap_b32 v9, v11
	global_store_dwordx4 v[0:1], v[8:11], off offset:64
	s_nop 1
	s_branch .LBB0_568
